# swa cache->state copy: ten loads in flight instead of a load-wait-store ladder, moved from the layer-0 W_out phase to the idle tails of the two layer-0 FFN-down phases
# baseline (speedup 1.0000x reference)
.LBB0_445:
	v_readlane_b32 s0, v240, 23
	s_cmp_eq_u32 s0, 1
	s_cselect_b64 vcc, -1, 0
	s_cmp_eq_u32 s0, 8
	v_readlane_b32 s2, v243, 56
	s_cselect_b64 s[0:1], -1, 0
	s_or_b64 s[0:1], s[0:1], vcc
	v_readlane_b32 s3, v243, 57
	s_and_b64 s[0:1], s[2:3], s[0:1]
	v_readlane_b32 s2, v240, 33
	v_readlane_b32 s3, v240, 34
	s_and_b64 s[0:1], s[2:3], s[0:1]
	s_andn2_b64 vcc, exec, s[0:1]
	s_cbranch_vccnz .LBB0_450
	v_mov_b32_e32 v2, v147
	v_readlane_b32 s0, v242, 6
	v_readlane_b32 s1, v242, 7
	v_ashrrev_i32_e32 v3, 31, v2
	s_mov_b64 s[8:9], s[88:89]
	v_lshl_add_u64 v[0:1], s[0:1], 0, v[2:3]
	s_mov_b64 s[0:1], 0xf0000
	s_mov_b64 s[10:11], s[90:91]
	s_mov_b64 s[12:13], s[92:93]
	s_mov_b64 s[14:15], s[94:95]
	v_cmp_gt_u64_e32 vcc, s[0:1], v[0:1]
	s_and_saveexec_b64 s[0:1], vcc
	v_readlane_b32 s80, v241, 40
	s_mov_b32 s6, 0x88888889
	v_readlane_b32 s86, v241, 46
	v_readlane_b32 s87, v241, 47
	v_readlane_b32 s88, v241, 48
	v_readlane_b32 s89, v241, 49
	v_readlane_b32 s7, v241, 30
	v_readlane_b32 s81, v241, 41
	v_readlane_b32 s82, v241, 42
	v_readlane_b32 s83, v241, 43
	v_readlane_b32 s84, v241, 44
	v_readlane_b32 s85, v241, 45
	v_readlane_b32 s90, v241, 50
	v_readlane_b32 s91, v241, 51
	v_readlane_b32 s92, v241, 52
	v_readlane_b32 s93, v241, 53
	v_readlane_b32 s94, v241, 54
	v_readlane_b32 s95, v241, 55
	s_cbranch_execz .LBB0_449
	v_readlane_b32 s2, v241, 33
	v_readlane_b32 s3, v240, 23
	s_nop 0
	v_add_lshl_u32 v2, s2, v2, 2
	s_cmp_eq_u32 s3, 1
	s_cselect_b32 s2, s86, s88
	s_cselect_b32 s3, s87, s89
	s_cselect_b32 s4, s30, s38
	s_cselect_b32 s5, s31, s39
	s_add_u32 s2, s2, 0x2000
	s_addc_u32 s3, s3, 0
	v_mov_b32_e32 v3, v2
	v_mul_hi_u32 v14, v3, s6
	v_lshrrev_b32_e32 v14, 14, v14
	v_lshl_add_u32 v3, v14, 11, v3
	v_lshlrev_b32_e32 v4, 2, v3
	global_load_dwordx4 v[20:23], v4, s[2:3]
	v_add_u32_e32 v3, 0x60000, v2
	v_mul_hi_u32 v14, v3, s6
	v_lshrrev_b32_e32 v14, 14, v14
	v_lshl_add_u32 v3, v14, 11, v3
	v_lshlrev_b32_e32 v5, 2, v3
	global_load_dwordx4 v[24:27], v5, s[2:3]
	v_add_u32_e32 v3, 0xc0000, v2
	v_mul_hi_u32 v14, v3, s6
	v_lshrrev_b32_e32 v14, 14, v14
	v_lshl_add_u32 v3, v14, 11, v3
	v_lshlrev_b32_e32 v6, 2, v3
	global_load_dwordx4 v[28:31], v6, s[2:3]
	v_add_u32_e32 v3, 0x120000, v2
	v_mul_hi_u32 v14, v3, s6
	v_lshrrev_b32_e32 v14, 14, v14
	v_lshl_add_u32 v3, v14, 11, v3
	v_lshlrev_b32_e32 v7, 2, v3
	global_load_dwordx4 v[32:35], v7, s[2:3]
	v_add_u32_e32 v3, 0x180000, v2
	v_mul_hi_u32 v14, v3, s6
	v_lshrrev_b32_e32 v14, 14, v14
	v_lshl_add_u32 v3, v14, 11, v3
	v_lshlrev_b32_e32 v8, 2, v3
	global_load_dwordx4 v[36:39], v8, s[2:3]
	v_add_u32_e32 v3, 0x1e0000, v2
	v_mul_hi_u32 v14, v3, s6
	v_lshrrev_b32_e32 v14, 14, v14
	v_lshl_add_u32 v3, v14, 11, v3
	v_lshlrev_b32_e32 v9, 2, v3
	global_load_dwordx4 v[40:43], v9, s[2:3]
	v_add_u32_e32 v3, 0x240000, v2
	v_mul_hi_u32 v14, v3, s6
	v_lshrrev_b32_e32 v14, 14, v14
	v_lshl_add_u32 v3, v14, 11, v3
	v_lshlrev_b32_e32 v10, 2, v3
	global_load_dwordx4 v[44:47], v10, s[2:3]
	v_add_u32_e32 v3, 0x2a0000, v2
	v_mul_hi_u32 v14, v3, s6
	v_lshrrev_b32_e32 v14, 14, v14
	v_lshl_add_u32 v3, v14, 11, v3
	v_lshlrev_b32_e32 v11, 2, v3
	global_load_dwordx4 v[48:51], v11, s[2:3]
	v_add_u32_e32 v3, 0x300000, v2
	v_mul_hi_u32 v14, v3, s6
	v_lshrrev_b32_e32 v14, 14, v14
	v_lshl_add_u32 v3, v14, 11, v3
	v_lshlrev_b32_e32 v12, 2, v3
	global_load_dwordx4 v[52:55], v12, s[2:3]
	v_add_u32_e32 v3, 0x360000, v2
	v_mul_hi_u32 v14, v3, s6
	v_lshrrev_b32_e32 v14, 14, v14
	v_lshl_add_u32 v3, v14, 11, v3
	v_lshlrev_b32_e32 v13, 2, v3
	global_load_dwordx4 v[56:59], v13, s[2:3]
	s_waitcnt vmcnt(9)
	global_store_dwordx4 v4, v[20:23], s[4:5]
	s_waitcnt vmcnt(9)
	global_store_dwordx4 v5, v[24:27], s[4:5]
	s_waitcnt vmcnt(9)
	global_store_dwordx4 v6, v[28:31], s[4:5]
	s_waitcnt vmcnt(9)
	global_store_dwordx4 v7, v[32:35], s[4:5]
	s_waitcnt vmcnt(9)
	global_store_dwordx4 v8, v[36:39], s[4:5]
	s_waitcnt vmcnt(9)
	global_store_dwordx4 v9, v[40:43], s[4:5]
	s_waitcnt vmcnt(9)
	global_store_dwordx4 v10, v[44:47], s[4:5]
	s_waitcnt vmcnt(9)
	global_store_dwordx4 v11, v[48:51], s[4:5]
	s_waitcnt vmcnt(9)
	global_store_dwordx4 v12, v[52:55], s[4:5]
	s_waitcnt vmcnt(9)
	global_store_dwordx4 v13, v[56:59], s[4:5]
